# attention KV loop edge: next-tile head setup moved out of the barrier-to-first-MFMA path (addresses before B4, scalar state in PV MFMA gaps, fast entry at first QK MFMA)
# speedup vs baseline: 1.0137x; 1.0137x over previous
.Lfh:
	s_setprio 1
	s_waitcnt lgkmcnt(0)
	v_mfma_f32_32x32x16_bf16 v[64:79], v[168:171], v[80:83], v[238:253]
	ds_read_b128 v[180:183], v237 offset:53248
	ds_read_b128 v[176:179], v237 offset:53280
	v_add_u32_e32 v172, vcc_lo, v229
	v_add_u32_e32 v218, vcc_lo, v233
	v_mfma_f32_32x32x16_bf16 v[64:79], v[160:163], v[84:87], v[64:79]
	ds_read_b128 v[196:199], v237 offset:57856
	ds_read_b128 v[188:191], v237 offset:62464
	v_mfma_f32_32x32x16_bf16 v[64:79], v[164:167], v[88:91], v[64:79]
	ds_read_b128 v[200:203], v217 offset:13824
	ds_read_b128 v[184:187], v217 offset:13856
	v_mfma_f32_32x32x16_bf16 v[64:79], v[152:155], v[92:95], v[64:79]
	ds_read_b128 v[204:207], v237 offset:57888
	ds_read_b128 v[192:195], v237 offset:62496
	v_mfma_f32_32x32x16_bf16 v[64:79], v[156:159], v[96:99], v[64:79]
	ds_read_b128 v[168:171], v172 offset:8704
	ds_read_b128 v[160:163], v172 offset:8736
	v_mfma_f32_32x32x16_bf16 v[64:79], v[128:131], v[100:103], v[64:79]
	ds_read_b128 v[164:167], v172 offset:8768
	ds_read_b128 v[152:155], v172 offset:8800
	v_mfma_f32_32x32x16_bf16 v[64:79], v[132:135], v[104:107], v[64:79]
	ds_read_b128 v[156:159], v172 offset:8832
	ds_read_b128 v[128:131], v172 offset:8864
	v_mfma_f32_32x32x16_bf16 v[64:79], v[136:139], v[108:111], v[64:79]
	ds_read_b128 v[132:135], v172 offset:8896
	ds_read_b128 v[136:139], v172 offset:8928
	v_mfma_f32_32x32x16_bf16 v[64:79], v[140:143], v[112:115], v[64:79]
	ds_read_b128 v[140:143], v218 offset:22016
	ds_read_b128 v[172:175], v218 offset:22112
	v_mfma_f32_32x32x16_bf16 v[64:79], v[144:147], v[116:119], v[64:79]
	ds_read_b128 v[144:147], v218 offset:22048
	v_mfma_f32_32x32x16_bf16 v[64:79], v[148:151], v[120:123], v[64:79]
	ds_read_b128 v[148:151], v218 offset:22080
	v_mfma_f32_32x32x16_bf16 v[64:79], v[208:211], v[124:127], v[64:79]
	s_setprio 0
	s_barrier
	s_and_b64 vcc, exec, s[68:69]
	s_cbranch_vccnz .Ldmq_end
	s_cmp_ge_u32 s85, 4
	s_cbranch_scc1 .Lxdq_y
	s_and_b32 s99, s34, 1
	s_mul_i32 s98, s99, 0x4800
	s_addk_i32 s98, 0x6800
	s_mulk_i32 s99, 0x6800
	s_add_i32 s99, s99, s44
	s_add_i32 s98, s98, s44
	s_lshl_b32 s94, s34, 18
	s_lshl_b32 s90, s34, 13
	s_lshl_b32 s91, s34, 7
	s_add_i32 m0, s99, 0x0
	v_add_u32_e32 v255, s94, v221
	global_load_lds_dwordx4 v255, s[8:9]
	s_add_i32 m0, s99, 0x1000
	v_add_u32_e32 v255, s94, v222
	global_load_lds_dwordx4 v255, s[8:9]
	s_add_i32 m0, s99, 0x2000
	v_add_u32_e32 v255, s94, v223
	global_load_lds_dwordx4 v255, s[8:9]
	s_add_i32 m0, s99, 0x3000
	v_add_u32_e32 v255, s94, v224
	global_load_lds_dwordx4 v255, s[8:9]
	s_lshl_b32 s92, s34, s95
	s_add_i32 m0, s99, 0x4000
	v_add_u32_e32 v255, s92, v225
	global_load_lds_dwordx4 v255, s[46:47]
	s_add_i32 m0, s99, 0x5000
	v_add_u32_e32 v255, s90, v226
	global_load_lds_dwordx4 v255, s[52:53]
	s_branch .Ldmq_end

.LBB0_1289:
	s_cmp_ge_i32 s35, s89
	s_waitcnt vmcnt(0) lgkmcnt(0)
	s_cselect_b64 vcc, -1, 0
	s_or_b64 s[68:69], vcc, s[68:69]
	s_andn2_b64 s[100:101], s[70:71], s[68:69]
	s_bitcmp1_b32 s34, 0
	s_cselect_b32 s99, 0x6800, 0
	s_cselect_b32 s98, 0x4800, 0
	v_add_u32_e32 v72, s99, v230
	v_add_u32_e32 v73, s99, v231
	v_add_u32_e32 v237, s98, v234
	v_add_u32_e32 v217, 0xd000, v237
	s_and_b64 vcc, exec, s[100:101]
	s_waitcnt vmcnt(0) lgkmcnt(0)
	s_barrier
	s_cbranch_vccz .Lpp_slow
	s_setprio 1
	v_mfma_f32_32x32x16_bf16 v[48:63], v[180:183], v[64:67], v[48:63]
	ds_read_b128 v[168:171], v72
	ds_read_b128 v[160:163], v72 offset:32
	v_mfma_f32_32x32x16_bf16 v[32:47], v[184:187], v[64:67], v[32:47]
	ds_read_b128 v[164:167], v72 offset:64
	ds_read_b128 v[152:155], v72 offset:96
	s_add_i32 s15, s15, 64
	s_mov_b32 s35, s34
	v_mfma_f32_32x32x16_bf16 v[16:31], v[192:195], v[64:67], v[16:31]
	ds_read_b128 v[156:159], v72 offset:128
	ds_read_b128 v[128:131], v72 offset:160
	s_add_i32 s34, s34, 1
	s_cmp_ge_u32 s34, s87
	v_mfma_f32_32x32x16_bf16 v[0:15], v[196:199], v[64:67], v[0:15]
	ds_read_b128 v[132:135], v72 offset:192
	ds_read_b128 v[136:139], v72 offset:224
	s_cselect_b64 s[68:69], -1, 0
	s_mov_b64 s[70:71], -1
	v_mfma_f32_32x32x16_bf16 v[48:63], v[176:179], v[68:71], v[48:63]
	ds_read_b128 v[140:143], v73 offset:17408
	ds_read_b128 v[144:147], v73 offset:17440
	s_mov_b32 vcc_lo, s99
	v_mfma_f32_32x32x16_bf16 v[32:47], v[200:203], v[68:71], v[32:47]
	ds_read_b128 v[148:151], v73 offset:17472
	ds_read_b128 v[208:211], v73 offset:17504
	v_mfma_f32_32x32x16_bf16 v[16:31], v[204:207], v[68:71], v[16:31]
	v_mfma_f32_32x32x16_bf16 v[0:15], v[188:191], v[68:71], v[0:15]
	s_branch .Lfh
